# GEMM-in epilogue: forget-gate log(f) as v_log_f32*ln2 (argument always normal, finite, positive; f32 throughout, f16 store unchanged)
# speedup vs baseline: 1.0118x; 1.0073x over previous
.LBB0_622:
	s_andn2_b64 vcc, exec, s[6:7]
	s_cbranch_vccnz .LBB0_624
	s_lshl_b32 s16, s12, 10
	s_lshl_b64 s[6:7], s[16:17], 2
	s_add_u32 s6, s66, s6
	s_addc_u32 s7, s67, s7
	s_add_u32 s74, s6, 0x1a1f000
	s_addc_u32 s75, s7, 0
	s_lshl_b32 s6, s97, 8
	s_and_b32 s6, s6, 0x300
	v_or_b32_e32 v146, s6, v174
	v_lshlrev_b32_e32 v166, 2, v146
	global_load_dwordx4 v[134:137], v166, s[74:75]
	global_load_dwordx4 v[130:133], v166, s[74:75] offset:16
	v_mul_f32_e32 v156, 0xbfb8aa3b, v126
	v_mul_f32_e32 v157, 0xbfb8aa3b, v127
	v_exp_f32_e32 v156, v156
	v_mul_f32_e32 v158, 0xbfb8aa3b, v128
	v_exp_f32_e32 v157, v157
	v_exp_f32_e32 v158, v158
	v_mul_f32_e32 v159, 0xbfb8aa3b, v129
	v_mul_f32_e32 v160, 0xbfb8aa3b, v122
	v_exp_f32_e32 v159, v159
	v_add_f32_e32 v156, 1.0, v156
	v_exp_f32_e32 v160, v160
	v_add_f32_e32 v157, 1.0, v157
	v_rcp_f32_e32 v156, v156
	v_add_f32_e32 v158, 1.0, v158
	v_rcp_f32_e32 v157, v157
	v_rcp_f32_e32 v158, v158
	v_add_f32_e32 v159, 1.0, v159
	v_add_f32_e32 v160, 1.0, v160
	v_rcp_f32_e32 v159, v159
	v_rcp_f32_e32 v160, v160
	v_mul_f32_e32 v161, 0xbfb8aa3b, v123
	v_exp_f32_e32 v161, v161
	v_lshlrev_b32_e32 v146, 1, v146
	v_lshl_add_u64 v[164:165], s[62:63], 0, v[146:147]
	v_lshl_add_u32 v162, s60, 8, v172
	v_add_f32_e32 v161, 1.0, v161
	v_rcp_f32_e32 v161, v161
	v_mul_f32_e32 v190, 0xbfb8aa3b, v61
	v_exp_f32_e32 v190, v190
	s_waitcnt vmcnt(0)
	v_sub_f32_e32 v180, 1.0, v134
	v_sub_f32_e32 v179, 1.0, v135
	v_fma_f32 v156, v156, v180, v134
	v_sub_f32_e32 v170, 1.0, v136
	v_fma_f32 v157, v157, v179, v135
	v_fma_f32 v158, v158, v170, v136
	v_sub_f32_e32 v168, 1.0, v137
	v_sub_f32_e32 v167, 1.0, v130
	v_fma_f32 v159, v159, v168, v137
	v_log_f32_e32 v156, v156
	v_fma_f32 v160, v160, v167, v130
	v_log_f32_e32 v157, v157
	v_log_f32_e32 v158, v158
	v_log_f32_e32 v159, v159
	v_sub_f32_e32 v146, 1.0, v131
	v_log_f32_e32 v160, v160
	v_mul_f32_e32 v156, 0x3f317217, v156
	v_mul_f32_e32 v157, 0x3f317217, v157
	v_mul_f32_e32 v163, 0x3f317217, v158
	v_cvt_pk_f16_f32 v158, v156, v157
	v_fma_f32 v156, v161, v146, v131
	v_mul_f32_e32 v161, 0xbfb8aa3b, v124
	v_log_f32_e32 v156, v156
	v_exp_f32_e32 v161, v161
	v_mul_f32_e32 v159, 0x3f317217, v159
	v_cvt_pk_f16_f32 v159, v163, v159
	v_mul_f32_e32 v157, 0x3f317217, v160
	v_add_f32_e32 v161, 1.0, v161
	v_mul_f32_e32 v163, 0xbfb8aa3b, v125
	v_rcp_f32_e32 v161, v161
	v_exp_f32_e32 v163, v163
	v_sub_f32_e32 v171, 1.0, v132
	v_sub_f32_e32 v169, 1.0, v133
	v_mul_f32_e32 v156, 0x3f317217, v156
	v_fma_f32 v160, v161, v171, v132
	v_add_f32_e32 v161, 1.0, v163
	v_rcp_f32_e32 v161, v161
	v_add_f32_e32 v190, 1.0, v190
	v_rcp_f32_e32 v190, v190
	v_log_f32_e32 v163, v160
	v_cvt_pk_f16_f32 v160, v157, v156
	v_fma_f32 v156, v161, v169, v133
	v_log_f32_e32 v156, v156
	v_mul_f32_e32 v157, 0x3f317217, v163
	v_mul_f32_e32 v161, 0xbfb8aa3b, v118
	v_exp_f32_e32 v163, v161
	v_mul_f32_e32 v156, 0x3f317217, v156
	v_cvt_pk_f16_f32 v161, v157, v156
	v_add_f32_e32 v156, 1.0, v163
	v_rcp_f32_e32 v181, v156
	v_mul_f32_e32 v156, 0xbfb8aa3b, v119
	v_exp_f32_e32 v182, v156
	v_ashrrev_i32_e32 v163, 31, v162
	v_lshlrev_b64 v[156:157], 11, v[162:163]
	v_fma_f32 v163, v181, v180, v134
	v_add_f32_e32 v181, 1.0, v182
	v_rcp_f32_e32 v181, v181
	v_lshl_add_u64 v[156:157], v[164:165], 0, v[156:157]
	global_store_dwordx4 v[156:157], v[158:161], off
	v_log_f32_e32 v163, v163
	s_nop 0
	v_fma_f32 v158, v181, v179, v135
	v_mul_f32_e32 v161, 0xbfb8aa3b, v120
	v_exp_f32_e32 v161, v161
	v_log_f32_e32 v158, v158
	v_add_f32_e32 v161, 1.0, v161
	v_rcp_f32_e32 v161, v161
	v_mul_f32_e32 v159, 0x3f317217, v163
	v_fma_f32 v161, v161, v170, v136
	v_mul_f32_e32 v163, 0xbfb8aa3b, v121
	v_exp_f32_e32 v163, v163
	v_log_f32_e32 v161, v161
	v_add_f32_e32 v163, 1.0, v163
	v_rcp_f32_e32 v163, v163
	v_mul_f32_e32 v158, 0x3f317217, v158
	v_cvt_pk_f16_f32 v182, v159, v158
	v_fma_f32 v158, v163, v168, v137
	v_mul_f32_e32 v163, 0xbfb8aa3b, v115
	v_mul_f32_e32 v159, 0x3f317217, v161
	v_mul_f32_e32 v161, 0xbfb8aa3b, v114
	v_exp_f32_e32 v161, v161
	v_log_f32_e32 v158, v158
	v_add_f32_e32 v161, 1.0, v161
	v_rcp_f32_e32 v161, v161
	s_nop 0
	v_fma_f32 v161, v161, v167, v130
	v_exp_f32_e32 v163, v163
	s_nop 0
	v_add_f32_e32 v163, 1.0, v163
	v_log_f32_e32 v161, v161
	v_rcp_f32_e32 v163, v163
	v_mul_f32_e32 v158, 0x3f317217, v158
	v_cvt_pk_f16_f32 v183, v159, v158
	v_fma_f32 v158, v163, v146, v131
	v_mul_f32_e32 v163, 0xbfb8aa3b, v117
	v_mul_f32_e32 v159, 0x3f317217, v161
	v_mul_f32_e32 v161, 0xbfb8aa3b, v116
	v_exp_f32_e32 v161, v161
	v_log_f32_e32 v158, v158
	v_add_f32_e32 v161, 1.0, v161
	v_rcp_f32_e32 v161, v161
	v_exp_f32_e32 v163, v163
	v_fma_f32 v161, v161, v171, v132
	v_add_f32_e32 v163, 1.0, v163
	v_rcp_f32_e32 v163, v163
	v_mul_f32_e32 v158, 0x3f317217, v158
	v_log_f32_e32 v161, v161
	v_cvt_pk_f16_f32 v184, v159, v158
	v_fma_f32 v158, v163, v169, v133
	v_log_f32_e32 v158, v158
	v_mul_f32_e32 v159, 0x3f317217, v161
	v_mul_f32_e32 v161, 0xbfb8aa3b, v110
	v_exp_f32_e32 v161, v161
	v_mul_f32_e32 v158, 0x3f317217, v158
	v_cvt_pk_f16_f32 v185, v159, v158
	v_add_f32_e32 v159, 1.0, v161
	v_rcp_f32_e32 v160, v159
	v_mul_f32_e32 v159, 0xbfb8aa3b, v111
	v_exp_f32_e32 v161, v159
	v_or_b32_e32 v158, 16, v162
	v_fma_f32 v160, v160, v180, v134
	v_add_f32_e32 v161, 1.0, v161
	v_rcp_f32_e32 v161, v161
	v_log_f32_e32 v160, v160
	v_fma_f32 v161, v161, v179, v135
	v_ashrrev_i32_e32 v159, 31, v158
	v_mul_f32_e32 v181, 0xbfb8aa3b, v112
	v_exp_f32_e32 v181, v181
	v_log_f32_e32 v161, v161
	v_lshlrev_b64 v[158:159], 11, v[158:159]
	v_lshl_add_u64 v[158:159], v[164:165], 0, v[158:159]
	v_add_f32_e32 v181, 1.0, v181
	global_store_dwordx4 v[158:159], v[182:185], off
	v_rcp_f32_e32 v181, v181
	s_nop 0
	v_mul_f32_e32 v182, 0xbfb8aa3b, v113
	v_mul_f32_e32 v160, 0x3f317217, v160
	v_exp_f32_e32 v182, v182
	v_fma_f32 v181, v181, v170, v136
	v_add_f32_e32 v182, 1.0, v182
	v_rcp_f32_e32 v183, v182
	v_log_f32_e32 v181, v181
	v_mul_f32_e32 v161, 0x3f317217, v161
	v_cvt_pk_f16_f32 v182, v160, v161
	v_fma_f32 v160, v183, v168, v137
	v_mul_f32_e32 v183, 0xbfb8aa3b, v107
	v_mul_f32_e32 v161, 0x3f317217, v181
	v_mul_f32_e32 v181, 0xbfb8aa3b, v106
	v_exp_f32_e32 v181, v181
	v_log_f32_e32 v160, v160
	v_add_f32_e32 v181, 1.0, v181
	v_rcp_f32_e32 v181, v181
	v_exp_f32_e32 v183, v183
	v_fma_f32 v181, v181, v167, v130
	v_add_f32_e32 v183, 1.0, v183
	v_rcp_f32_e32 v184, v183
	v_log_f32_e32 v181, v181
	v_mul_f32_e32 v160, 0x3f317217, v160
	v_cvt_pk_f16_f32 v183, v161, v160
	v_fma_f32 v160, v184, v146, v131
	v_mul_f32_e32 v184, 0xbfb8aa3b, v109
	v_mul_f32_e32 v161, 0x3f317217, v181
	v_mul_f32_e32 v181, 0xbfb8aa3b, v108
	v_exp_f32_e32 v181, v181
	v_log_f32_e32 v160, v160
	v_add_f32_e32 v181, 1.0, v181
	v_rcp_f32_e32 v181, v181
	v_exp_f32_e32 v184, v184
	v_fma_f32 v181, v181, v171, v132
	v_add_f32_e32 v184, 1.0, v184
	v_rcp_f32_e32 v185, v184
	v_mul_f32_e32 v160, 0x3f317217, v160
	v_log_f32_e32 v181, v181
	v_cvt_pk_f16_f32 v184, v161, v160
	v_fma_f32 v160, v185, v169, v133
	v_log_f32_e32 v160, v160
	v_mul_f32_e32 v161, 0x3f317217, v181
	v_mul_f32_e32 v181, 0xbfb8aa3b, v102
	v_exp_f32_e32 v181, v181
	v_mul_f32_e32 v160, 0x3f317217, v160
	v_cvt_pk_f16_f32 v185, v161, v160
	v_add_f32_e32 v161, 1.0, v181
	v_rcp_f32_e32 v163, v161
	v_mul_f32_e32 v161, 0xbfb8aa3b, v103
	v_exp_f32_e32 v181, v161
	v_or_b32_e32 v160, 32, v162
	v_fma_f32 v163, v163, v180, v134
	v_add_f32_e32 v181, 1.0, v181
	v_rcp_f32_e32 v181, v181
	v_ashrrev_i32_e32 v161, 31, v160
	v_lshlrev_b64 v[160:161], 11, v[160:161]
	v_fma_f32 v181, v181, v179, v135
	v_log_f32_e32 v163, v163
	v_lshl_add_u64 v[160:161], v[164:165], 0, v[160:161]
	global_store_dwordx4 v[160:161], v[182:185], off
	v_or_b32_e32 v162, 48, v162
	s_nop 0
	v_mul_f32_e32 v183, 0xbfb8aa3b, v104
	v_exp_f32_e32 v183, v183
	v_log_f32_e32 v181, v181
	v_mul_f32_e32 v184, 0xbfb8aa3b, v105
	v_exp_f32_e32 v184, v184
	v_add_f32_e32 v183, 1.0, v183
	v_rcp_f32_e32 v183, v183
	v_mul_f32_e32 v163, 0x3f317217, v163
	v_add_f32_e32 v184, 1.0, v184
	v_rcp_f32_e32 v184, v184
	v_fma_f32 v183, v183, v170, v136
	s_nop 0
	v_mul_f32_e32 v181, 0x3f317217, v181
	v_cvt_pk_f16_f32 v182, v163, v181
	v_fma_f32 v163, v184, v168, v137
	v_log_f32_e32 v183, v183
	v_mul_f32_e32 v185, 0xbfb8aa3b, v99
	v_exp_f32_e32 v185, v185
	v_mul_f32_e32 v184, 0xbfb8aa3b, v98
	v_exp_f32_e32 v184, v184
	v_log_f32_e32 v163, v163
	v_add_f32_e32 v184, 1.0, v184
	v_rcp_f32_e32 v184, v184
	v_mul_f32_e32 v181, 0x3f317217, v183
	v_add_f32_e32 v185, 1.0, v185
	v_rcp_f32_e32 v185, v185
	v_fma_f32 v184, v184, v167, v130
	s_nop 0
	v_mul_f32_e32 v163, 0x3f317217, v163
	v_cvt_pk_f16_f32 v183, v181, v163
	v_fma_f32 v163, v185, v146, v131
	v_log_f32_e32 v184, v184
	v_mul_f32_e32 v186, 0xbfb8aa3b, v101
	v_exp_f32_e32 v186, v186
	v_mul_f32_e32 v185, 0xbfb8aa3b, v100
	v_exp_f32_e32 v185, v185
	v_log_f32_e32 v163, v163
	v_add_f32_e32 v185, 1.0, v185
	v_rcp_f32_e32 v185, v185
	v_mul_f32_e32 v181, 0x3f317217, v184
	v_fma_f32 v185, v185, v171, v132
	v_add_f32_e32 v186, 1.0, v186
	v_rcp_f32_e32 v186, v186
	v_mul_f32_e32 v163, 0x3f317217, v163
	v_log_f32_e32 v185, v185
	v_cvt_pk_f16_f32 v184, v181, v163
	v_fma_f32 v163, v186, v169, v133
	v_log_f32_e32 v163, v163
	v_mul_f32_e32 v186, 0xbfb8aa3b, v94
	v_exp_f32_e32 v186, v186
	v_mul_f32_e32 v181, 0x3f317217, v185
	s_nop 1
	v_mul_f32_e32 v163, 0x3f317217, v163
	v_cvt_pk_f16_f32 v185, v181, v163
	v_add_f32_e32 v163, 1.0, v186
	v_rcp_f32_e32 v181, v163
	v_mul_f32_e32 v163, 0xbfb8aa3b, v95
	v_exp_f32_e32 v186, v163
	v_ashrrev_i32_e32 v163, 31, v162
	v_fma_f32 v181, v181, v180, v134
	v_add_f32_e32 v186, 1.0, v186
	v_rcp_f32_e32 v186, v186
	v_lshlrev_b64 v[162:163], 11, v[162:163]
	v_lshl_add_u64 v[162:163], v[164:165], 0, v[162:163]
	v_fma_f32 v164, v186, v179, v135
	v_log_f32_e32 v181, v181
	global_store_dwordx4 v[162:163], v[182:185], off
	s_nop 0
	s_nop 0
	v_mul_f32_e32 v182, 0xbfb8aa3b, v96
	v_exp_f32_e32 v182, v182
	v_log_f32_e32 v164, v164
	v_add_f32_e32 v182, 1.0, v182
	v_mul_f32_e32 v183, 0xbfb8aa3b, v97
	v_mul_f32_e32 v165, 0x3f317217, v181
	v_rcp_f32_e32 v182, v182
	v_exp_f32_e32 v183, v183
	v_fma_f32 v182, v182, v170, v136
	v_add_f32_e32 v183, 1.0, v183
	v_rcp_f32_e32 v183, v183
	v_mul_f32_e32 v164, 0x3f317217, v164
	v_log_f32_e32 v184, v182
	v_cvt_pk_f16_f32 v182, v165, v164
	v_fma_f32 v164, v183, v168, v137
	v_mul_f32_e32 v183, 0xbfb8aa3b, v90
	v_exp_f32_e32 v183, v183
	v_log_f32_e32 v164, v164
	v_add_f32_e32 v183, 1.0, v183
	v_mul_f32_e32 v165, 0x3f317217, v184
	v_rcp_f32_e32 v183, v183
	v_mul_f32_e32 v184, 0xbfb8aa3b, v91
	v_exp_f32_e32 v184, v184
	v_fma_f32 v183, v183, v167, v130
	v_add_f32_e32 v184, 1.0, v184
	v_rcp_f32_e32 v184, v184
	v_log_f32_e32 v185, v183
	v_mul_f32_e32 v164, 0x3f317217, v164
	v_cvt_pk_f16_f32 v183, v165, v164
	v_fma_f32 v164, v184, v146, v131
	v_mul_f32_e32 v184, 0xbfb8aa3b, v92
	v_exp_f32_e32 v184, v184
	v_log_f32_e32 v164, v164
	v_add_f32_e32 v184, 1.0, v184
	v_mul_f32_e32 v165, 0x3f317217, v185
	v_mul_f32_e32 v185, 0xbfb8aa3b, v93
	v_rcp_f32_e32 v184, v184
	v_exp_f32_e32 v185, v185
	v_fma_f32 v184, v184, v171, v132
	v_add_f32_e32 v185, 1.0, v185
	v_rcp_f32_e32 v185, v185
	v_mul_f32_e32 v164, 0x3f317217, v164
	v_log_f32_e32 v186, v184
	v_cvt_pk_f16_f32 v184, v165, v164
	v_fma_f32 v164, v185, v169, v133
	v_log_f32_e32 v164, v164
	v_mul_f32_e32 v185, 0xbfb8aa3b, v86
	v_exp_f32_e32 v185, v185
	s_nop 0
	v_add_f32_e32 v185, 1.0, v185
	v_mul_f32_e32 v165, 0x3f317217, v186
	v_rcp_f32_e32 v186, v185
	v_mul_f32_e32 v185, 0xbfb8aa3b, v87
	v_exp_f32_e32 v187, v185
	s_nop 0
	v_mul_f32_e32 v164, 0x3f317217, v164
	v_cvt_pk_f16_f32 v185, v165, v164
	v_fma_f32 v164, v186, v180, v134
	v_add_f32_e32 v165, 1.0, v187
	v_rcp_f32_e32 v181, v165
	s_nop 0
	v_log_f32_e32 v186, v164
	v_add_co_u32_e64 v164, s[6:7], s89, v156
	s_nop 0
	s_nop 0
	v_addc_co_u32_e64 v165, s[6:7], 0, v157, s[6:7]
	global_store_dwordx4 v[164:165], v[182:185], off
	v_fma_f32 v164, v181, v179, v135
	s_nop 0
	v_mul_f32_e32 v182, 0xbfb8aa3b, v88
	v_exp_f32_e32 v182, v182
	v_log_f32_e32 v164, v164
	v_add_f32_e32 v182, 1.0, v182
	v_mul_f32_e32 v183, 0xbfb8aa3b, v89
	v_rcp_f32_e32 v182, v182
	v_exp_f32_e32 v183, v183
	v_mul_f32_e32 v165, 0x3f317217, v186
	v_fma_f32 v182, v182, v170, v136
	v_add_f32_e32 v183, 1.0, v183
	v_rcp_f32_e32 v183, v183
	v_mul_f32_e32 v164, 0x3f317217, v164
	v_log_f32_e32 v184, v182
	v_cvt_pk_f16_f32 v182, v165, v164
	v_fma_f32 v164, v183, v168, v137
	v_mul_f32_e32 v183, 0xbfb8aa3b, v82
	v_exp_f32_e32 v183, v183
	v_log_f32_e32 v164, v164
	v_add_f32_e32 v183, 1.0, v183
	v_mul_f32_e32 v165, 0x3f317217, v184
	v_rcp_f32_e32 v183, v183
	v_mul_f32_e32 v184, 0xbfb8aa3b, v83
	v_exp_f32_e32 v184, v184
	v_fma_f32 v183, v183, v167, v130
	v_add_f32_e32 v184, 1.0, v184
	v_rcp_f32_e32 v184, v184
	v_log_f32_e32 v185, v183
	v_mul_f32_e32 v164, 0x3f317217, v164
	v_cvt_pk_f16_f32 v183, v165, v164
	v_fma_f32 v164, v184, v146, v131
	v_mul_f32_e32 v184, 0xbfb8aa3b, v84
	v_exp_f32_e32 v184, v184
	v_log_f32_e32 v164, v164
	v_add_f32_e32 v184, 1.0, v184
	v_mul_f32_e32 v165, 0x3f317217, v185
	v_mul_f32_e32 v185, 0xbfb8aa3b, v85
	v_rcp_f32_e32 v184, v184
	v_exp_f32_e32 v185, v185
	v_fma_f32 v184, v184, v171, v132
	v_add_f32_e32 v185, 1.0, v185
	v_rcp_f32_e32 v185, v185
	v_mul_f32_e32 v164, 0x3f317217, v164
	v_log_f32_e32 v186, v184
	v_cvt_pk_f16_f32 v184, v165, v164
	v_fma_f32 v164, v185, v169, v133
	v_log_f32_e32 v164, v164
	v_mul_f32_e32 v185, 0xbfb8aa3b, v78
	v_exp_f32_e32 v185, v185
	s_nop 0
	v_add_f32_e32 v185, 1.0, v185
	v_mul_f32_e32 v165, 0x3f317217, v186
	v_rcp_f32_e32 v186, v185
	v_mul_f32_e32 v185, 0xbfb8aa3b, v79
	v_exp_f32_e32 v187, v185
	s_nop 0
	v_mul_f32_e32 v164, 0x3f317217, v164
	v_cvt_pk_f16_f32 v185, v165, v164
	v_fma_f32 v164, v186, v180, v134
	v_add_f32_e32 v165, 1.0, v187
	v_rcp_f32_e32 v181, v165
	s_nop 0
	v_log_f32_e32 v186, v164
	v_add_co_u32_e64 v164, s[6:7], s90, v156
	s_nop 0
	s_nop 0
	v_addc_co_u32_e64 v165, s[6:7], 0, v157, s[6:7]
	global_store_dwordx4 v[164:165], v[182:185], off
	v_fma_f32 v164, v181, v179, v135
	s_nop 0
	v_mul_f32_e32 v182, 0xbfb8aa3b, v80
	v_exp_f32_e32 v182, v182
	v_log_f32_e32 v164, v164
	v_add_f32_e32 v182, 1.0, v182
	v_mul_f32_e32 v183, 0xbfb8aa3b, v81
	v_rcp_f32_e32 v182, v182
	v_exp_f32_e32 v183, v183
	v_mul_f32_e32 v165, 0x3f317217, v186
	v_fma_f32 v182, v182, v170, v136
	v_add_f32_e32 v183, 1.0, v183
	v_rcp_f32_e32 v183, v183
	v_mul_f32_e32 v164, 0x3f317217, v164
	v_log_f32_e32 v184, v182
	v_cvt_pk_f16_f32 v182, v165, v164
	v_fma_f32 v164, v183, v168, v137
	v_mul_f32_e32 v183, 0xbfb8aa3b, v74
	v_exp_f32_e32 v183, v183
	v_log_f32_e32 v164, v164
	v_add_f32_e32 v183, 1.0, v183
	v_mul_f32_e32 v165, 0x3f317217, v184
	v_rcp_f32_e32 v183, v183
	v_mul_f32_e32 v184, 0xbfb8aa3b, v75
	v_exp_f32_e32 v184, v184
	v_fma_f32 v183, v183, v167, v130
	v_add_f32_e32 v184, 1.0, v184
	v_rcp_f32_e32 v184, v184
	v_log_f32_e32 v185, v183
	v_mul_f32_e32 v164, 0x3f317217, v164
	v_cvt_pk_f16_f32 v183, v165, v164
	v_fma_f32 v164, v184, v146, v131
	v_mul_f32_e32 v184, 0xbfb8aa3b, v76
	v_exp_f32_e32 v184, v184
	v_log_f32_e32 v164, v164
	v_add_f32_e32 v184, 1.0, v184
	v_mul_f32_e32 v165, 0x3f317217, v185
	v_mul_f32_e32 v185, 0xbfb8aa3b, v77
	v_rcp_f32_e32 v184, v184
	v_exp_f32_e32 v185, v185
	v_fma_f32 v184, v184, v171, v132
	v_add_f32_e32 v185, 1.0, v185
	v_rcp_f32_e32 v185, v185
	v_mul_f32_e32 v164, 0x3f317217, v164
	v_log_f32_e32 v186, v184
	v_cvt_pk_f16_f32 v184, v165, v164
	v_fma_f32 v164, v185, v169, v133
	v_mul_f32_e32 v185, 0xbfb8aa3b, v70
	v_log_f32_e32 v164, v164
	v_exp_f32_e32 v185, v185
	s_nop 0
	v_add_f32_e32 v185, 1.0, v185
	v_mul_f32_e32 v165, 0x3f317217, v186
	v_rcp_f32_e32 v186, v185
	v_mul_f32_e32 v185, 0xbfb8aa3b, v71
	v_exp_f32_e32 v187, v185
	v_fma_f32 v134, v186, v180, v134
	s_nop 0
	v_mul_f32_e32 v164, 0x3f317217, v164
	v_cvt_pk_f16_f32 v185, v165, v164
	v_add_f32_e32 v164, 1.0, v187
	v_rcp_f32_e32 v180, v164
	v_mul_f32_e32 v187, 0xbfb8aa3b, v59
	v_exp_f32_e32 v187, v187
	v_add_co_u32_e64 v164, s[6:7], s91, v156
	v_fma_f32 v135, v180, v179, v135
	s_nop 0
	v_addc_co_u32_e64 v165, s[6:7], 0, v157, s[6:7]
	global_store_dwordx4 v[164:165], v[182:185], off
	v_log_f32_e32 v134, v134
	v_mul_f32_e32 v165, 0xbfb8aa3b, v72
	v_exp_f32_e32 v165, v165
	v_mul_f32_e32 v179, 0xbfb8aa3b, v73
	v_exp_f32_e32 v179, v179
	v_add_f32_e32 v165, 1.0, v165
	v_rcp_f32_e32 v165, v165
	v_log_f32_e32 v135, v135
	v_fma_f32 v136, v165, v170, v136
	v_add_f32_e32 v165, 1.0, v179
	v_mul_f32_e32 v134, 0x3f317217, v134
	v_rcp_f32_e32 v165, v165
	s_nop 0
	v_fmac_f32_e32 v137, v165, v168
	v_mul_f32_e32 v165, 0xbfb8aa3b, v67
	v_mul_f32_e32 v135, 0x3f317217, v135
	v_log_f32_e32 v136, v136
	v_mul_f32_e32 v164, 0xbfb8aa3b, v66
	v_exp_f32_e32 v164, v164
	v_cvt_pk_f16_f32 v134, v134, v135
	v_log_f32_e32 v137, v137
	v_add_f32_e32 v164, 1.0, v164
	v_rcp_f32_e32 v164, v164
	v_exp_f32_e32 v165, v165
	v_fma_f32 v130, v164, v167, v130
	v_add_f32_e32 v164, 1.0, v165
	v_mul_f32_e32 v135, 0x3f317217, v136
	v_rcp_f32_e32 v164, v164
	v_mul_f32_e32 v184, 0xbfb8aa3b, v65
	v_fma_f32 v131, v164, v146, v131
	v_mul_f32_e32 v136, 0x3f317217, v137
	v_log_f32_e32 v130, v130
	v_mul_f32_e32 v137, 0xbfb8aa3b, v68
	v_exp_f32_e32 v137, v137
	v_cvt_pk_f16_f32 v135, v135, v136
	v_log_f32_e32 v131, v131
	v_add_f32_e32 v137, 1.0, v137
	v_mul_f32_e32 v146, 0xbfb8aa3b, v69
	v_rcp_f32_e32 v137, v137
	v_exp_f32_e32 v146, v146
	v_mul_f32_e32 v130, 0x3f317217, v130
	v_fma_f32 v132, v137, v171, v132
	v_add_f32_e32 v137, 1.0, v146
	v_rcp_f32_e32 v137, v137
	v_mul_f32_e32 v131, 0x3f317217, v131
	v_log_f32_e32 v132, v132
	v_fmac_f32_e32 v133, v137, v169
	v_cmp_gt_f32_e64 s[6:7], s93, v133
	v_cvt_pk_f16_f32 v136, v130, v131
	s_nop 0
	v_cndmask_b32_e64 v131, 0, 32, s[6:7]
	v_ldexp_f32 v131, v133, v131
	v_log_f32_e32 v131, v131
	v_exp_f32_e32 v184, v184
	v_add_f32_e32 v187, 1.0, v187
	v_mul_f32_e32 v130, 0x3f317217, v132
	v_mul_f32_e32 v132, 0x3f317217, v131
	v_fma_f32 v132, v131, s94, -v132
	v_fmac_f32_e32 v132, 0x3377d1cf, v131
	v_fmac_f32_e32 v132, 0x3f317217, v131
	v_cmp_lt_f32_e64 vcc, |v131|, s95
	v_add_f32_e32 v184, 1.0, v184
	v_rcp_f32_e32 v184, v184
	v_cndmask_b32_e32 v131, v131, v132, vcc
	v_cndmask_b32_e64 v132, 0, v178, s[6:7]
	v_sub_f32_e32 v131, v131, v132
	v_cvt_pk_f16_f32 v137, v130, v131
	v_add_co_u32_e32 v130, vcc, s92, v156
	v_rcp_f32_e32 v188, v187
	s_nop 0
	v_addc_co_u32_e32 v131, vcc, 0, v157, vcc
	global_store_dwordx4 v[130:131], v[134:137], off
	v_or_b32_e32 v130, 0x200, v166
	global_load_dwordx4 v[134:137], v130, s[74:75]
	v_mul_f32_e32 v131, 0xbfb8aa3b, v62
	v_exp_f32_e32 v146, v131
	global_load_dwordx4 v[130:133], v130, s[74:75] offset:16
	v_lshl_add_u64 v[170:171], v[156:157], 0, s[18:19]
	v_lshl_add_u64 v[168:169], v[156:157], 0, s[42:43]
	v_add_f32_e32 v146, 1.0, v146
	v_rcp_f32_e32 v164, v146
	v_mul_f32_e32 v146, 0xbfb8aa3b, v63
	v_exp_f32_e32 v165, v146
	v_lshl_add_u64 v[166:167], v[156:157], 0, s[48:49]
	v_add_f32_e32 v165, 1.0, v165
	v_rcp_f32_e32 v180, v165
	s_waitcnt vmcnt(1)
	v_sub_f32_e32 v146, 1.0, v134
	v_fma_f32 v164, v164, v146, v134
	v_sub_f32_e32 v179, 1.0, v135
	v_fma_f32 v180, v180, v179, v135
	v_log_f32_e32 v181, v164
	v_lshl_add_u64 v[164:165], v[156:157], 0, s[52:53]
	v_log_f32_e32 v180, v180
	v_mul_f32_e32 v183, 0xbfb8aa3b, v64
	v_exp_f32_e32 v183, v183
	s_nop 0
	v_add_f32_e32 v183, 1.0, v183
	s_nop 0
	v_mul_f32_e32 v182, 0x3f317217, v181
	v_rcp_f32_e32 v183, v183
	s_nop 1
	v_mul_f32_e32 v180, 0x3f317217, v180
	v_sub_f32_e32 v181, 1.0, v136
	v_fma_f32 v183, v183, v181, v136
	v_cvt_pk_f16_f32 v186, v182, v180
	v_sub_f32_e32 v180, 1.0, v137
	v_log_f32_e32 v183, v183
	v_fma_f32 v182, v184, v180, v137
	s_nop 0
	v_log_f32_e32 v182, v182
	v_mul_f32_e32 v185, 0xbfb8aa3b, v58
	v_exp_f32_e32 v185, v185
	s_nop 0
	v_add_f32_e32 v185, 1.0, v185
	s_nop 0
	v_mul_f32_e32 v183, 0x3f317217, v183
	v_rcp_f32_e32 v185, v185
	s_nop 1
	v_mul_f32_e32 v184, 0x3f317217, v182
	s_waitcnt vmcnt(0)
	v_sub_f32_e32 v182, 1.0, v130
	v_fma_f32 v185, v185, v182, v130
	s_nop 1
	v_log_f32_e32 v185, v185
	v_cvt_pk_f16_f32 v187, v183, v184
	v_sub_f32_e32 v183, 1.0, v131
	v_fma_f32 v184, v188, v183, v131
	v_log_f32_e32 v184, v184
	v_mul_f32_e32 v189, 0xbfb8aa3b, v60
	v_exp_f32_e32 v189, v189
	s_nop 0
	v_add_f32_e32 v189, 1.0, v189
	s_nop 0
	v_mul_f32_e32 v188, 0x3f317217, v185
	v_rcp_f32_e32 v189, v189
	s_nop 1
	v_mul_f32_e32 v184, 0x3f317217, v184
	v_sub_f32_e32 v185, 1.0, v132
	v_fma_f32 v189, v189, v185, v132
	v_cvt_pk_f16_f32 v188, v188, v184
	v_sub_f32_e32 v184, 1.0, v133
	v_log_f32_e32 v189, v189
	v_fma_f32 v190, v190, v184, v133
	s_nop 0
	v_log_f32_e32 v190, v190
	v_mul_f32_e32 v192, 0xbfb8aa3b, v54
	v_exp_f32_e32 v192, v192
	v_mul_f32_e32 v189, 0x3f317217, v189
	s_nop 0
	v_add_f32_e32 v191, 1.0, v192
	v_mul_f32_e32 v192, 0xbfb8aa3b, v55
	v_rcp_f32_e32 v191, v191
	v_exp_f32_e32 v192, v192
	v_mul_f32_e32 v190, 0x3f317217, v190
	v_cvt_pk_f16_f32 v189, v189, v190
	v_fma_f32 v191, v191, v146, v134
	v_add_f32_e32 v192, 1.0, v192
	v_rcp_f32_e32 v192, v192
	global_store_dwordx4 v[156:157], v[186:189], off offset:256
	v_fma_f32 v156, v192, v179, v135
	v_log_f32_e32 v191, v191
	v_mul_f32_e32 v187, 0xbfb8aa3b, v56
	v_exp_f32_e32 v187, v187
	v_log_f32_e32 v156, v156
	v_mul_f32_e32 v188, 0xbfb8aa3b, v57
	v_exp_f32_e32 v188, v188
	v_add_f32_e32 v187, 1.0, v187
	v_rcp_f32_e32 v187, v187
	v_mul_f32_e32 v157, 0x3f317217, v191
	v_add_f32_e32 v188, 1.0, v188
	v_rcp_f32_e32 v188, v188
	v_fma_f32 v187, v187, v181, v136
	s_nop 0
	v_mul_f32_e32 v156, 0x3f317217, v156
	v_cvt_pk_f16_f32 v186, v157, v156
	v_fma_f32 v156, v188, v180, v137
	v_log_f32_e32 v187, v187
	v_mul_f32_e32 v189, 0xbfb8aa3b, v51
	v_exp_f32_e32 v189, v189
	v_mul_f32_e32 v188, 0xbfb8aa3b, v50
	v_exp_f32_e32 v188, v188
	v_log_f32_e32 v156, v156
	v_add_f32_e32 v188, 1.0, v188
	v_rcp_f32_e32 v188, v188
	v_mul_f32_e32 v157, 0x3f317217, v187
	v_add_f32_e32 v189, 1.0, v189
	v_rcp_f32_e32 v189, v189
	v_fma_f32 v188, v188, v182, v130
	s_nop 0
	v_mul_f32_e32 v156, 0x3f317217, v156
	v_cvt_pk_f16_f32 v187, v157, v156
	v_fma_f32 v156, v189, v183, v131
	v_log_f32_e32 v188, v188
	v_mul_f32_e32 v190, 0xbfb8aa3b, v53
	v_exp_f32_e32 v190, v190
	v_mul_f32_e32 v189, 0xbfb8aa3b, v52
	v_exp_f32_e32 v189, v189
	v_log_f32_e32 v156, v156
	v_add_f32_e32 v189, 1.0, v189
	v_rcp_f32_e32 v189, v189
	v_mul_f32_e32 v157, 0x3f317217, v188
	v_fma_f32 v189, v189, v185, v132
	v_add_f32_e32 v190, 1.0, v190
	v_rcp_f32_e32 v190, v190
	v_mul_f32_e32 v156, 0x3f317217, v156
	v_log_f32_e32 v189, v189
	v_cvt_pk_f16_f32 v188, v157, v156
	v_fma_f32 v156, v190, v184, v133
	v_log_f32_e32 v156, v156
	v_mul_f32_e32 v190, 0xbfb8aa3b, v46
	v_exp_f32_e32 v190, v190
	v_mul_f32_e32 v157, 0x3f317217, v189
	s_nop 0
	v_add_f32_e32 v189, 1.0, v190
	v_mul_f32_e32 v190, 0xbfb8aa3b, v47
	v_rcp_f32_e32 v189, v189
	v_exp_f32_e32 v190, v190
	v_mul_f32_e32 v156, 0x3f317217, v156
	v_fma_f32 v189, v189, v146, v134
	v_add_f32_e32 v190, 1.0, v190
	v_rcp_f32_e32 v190, v190
	s_nop 1
	v_log_f32_e32 v191, v189
	v_cvt_pk_f16_f32 v189, v157, v156
	v_fma_f32 v156, v190, v179, v135
	global_store_dwordx4 v[158:159], v[186:189], off offset:256
	v_mul_f32_e32 v159, 0xbfb8aa3b, v48
	v_exp_f32_e32 v159, v159
	v_log_f32_e32 v156, v156
	v_mul_f32_e32 v186, 0xbfb8aa3b, v49
	v_exp_f32_e32 v186, v186
	v_add_f32_e32 v159, 1.0, v159
	v_rcp_f32_e32 v159, v159
	v_mul_f32_e32 v157, 0x3f317217, v191
	v_add_f32_e32 v186, 1.0, v186
	v_rcp_f32_e32 v186, v186
	v_fma_f32 v159, v159, v181, v136
	s_nop 0
	v_mul_f32_e32 v156, 0x3f317217, v156
	v_cvt_pk_f16_f32 v156, v157, v156
	v_fma_f32 v157, v186, v180, v137
	v_log_f32_e32 v159, v159
	v_mul_f32_e32 v187, 0xbfb8aa3b, v43
	v_exp_f32_e32 v187, v187
	v_mul_f32_e32 v186, 0xbfb8aa3b, v42
	v_exp_f32_e32 v186, v186
	v_log_f32_e32 v157, v157
	v_add_f32_e32 v186, 1.0, v186
	v_rcp_f32_e32 v186, v186
	v_mul_f32_e32 v158, 0x3f317217, v159
	v_add_f32_e32 v187, 1.0, v187
	v_rcp_f32_e32 v187, v187
	v_fma_f32 v186, v186, v182, v130
	s_nop 0
	v_mul_f32_e32 v157, 0x3f317217, v157
	v_cvt_pk_f16_f32 v157, v158, v157
	v_fma_f32 v158, v187, v183, v131
	v_log_f32_e32 v186, v186
	v_mul_f32_e32 v188, 0xbfb8aa3b, v45
	v_exp_f32_e32 v188, v188
	v_mul_f32_e32 v187, 0xbfb8aa3b, v44
	v_exp_f32_e32 v187, v187
	v_log_f32_e32 v158, v158
	v_add_f32_e32 v187, 1.0, v187
	v_rcp_f32_e32 v187, v187
	v_mul_f32_e32 v159, 0x3f317217, v186
	v_fma_f32 v187, v187, v185, v132
	v_add_f32_e32 v188, 1.0, v188
	v_rcp_f32_e32 v188, v188
	v_mul_f32_e32 v158, 0x3f317217, v158
	v_log_f32_e32 v187, v187
	v_cvt_pk_f16_f32 v158, v159, v158
	v_fma_f32 v159, v188, v184, v133
	v_log_f32_e32 v159, v159
	v_mul_f32_e32 v188, 0xbfb8aa3b, v38
	v_exp_f32_e32 v188, v188
	v_mul_f32_e32 v186, 0x3f317217, v187
	s_nop 0
	v_add_f32_e32 v187, 1.0, v188
	v_mul_f32_e32 v188, 0xbfb8aa3b, v39
	v_rcp_f32_e32 v187, v187
	v_exp_f32_e32 v188, v188
	v_mul_f32_e32 v159, 0x3f317217, v159
	v_cvt_pk_f16_f32 v159, v186, v159
	v_fma_f32 v187, v187, v146, v134
	v_add_f32_e32 v188, 1.0, v188
	v_rcp_f32_e32 v188, v188
	global_store_dwordx4 v[160:161], v[156:159], off offset:256
	v_mul_f32_e32 v160, 0xbfb8aa3b, v41
	v_log_f32_e32 v187, v187
	v_fma_f32 v156, v188, v179, v135
	v_mul_f32_e32 v159, 0xbfb8aa3b, v40
	v_exp_f32_e32 v159, v159
	v_log_f32_e32 v156, v156
	v_exp_f32_e32 v160, v160
	v_add_f32_e32 v159, 1.0, v159
	v_rcp_f32_e32 v159, v159
	v_mul_f32_e32 v157, 0x3f317217, v187
	v_add_f32_e32 v160, 1.0, v160
	v_rcp_f32_e32 v160, v160
	v_fma_f32 v159, v159, v181, v136
	s_nop 0
	v_mul_f32_e32 v156, 0x3f317217, v156
	v_cvt_pk_f16_f32 v156, v157, v156
	v_fma_f32 v157, v160, v180, v137
	v_log_f32_e32 v159, v159
	v_mul_f32_e32 v161, 0xbfb8aa3b, v35
	v_exp_f32_e32 v161, v161
	v_mul_f32_e32 v160, 0xbfb8aa3b, v34
	v_exp_f32_e32 v160, v160
	v_log_f32_e32 v157, v157
	v_add_f32_e32 v160, 1.0, v160
	v_rcp_f32_e32 v160, v160
	v_mul_f32_e32 v158, 0x3f317217, v159
	v_add_f32_e32 v161, 1.0, v161
	v_rcp_f32_e32 v161, v161
	v_fma_f32 v160, v160, v182, v130
	s_nop 0
	v_mul_f32_e32 v157, 0x3f317217, v157
	v_cvt_pk_f16_f32 v157, v158, v157
	v_fma_f32 v158, v161, v183, v131
	v_log_f32_e32 v160, v160
	v_mul_f32_e32 v186, 0xbfb8aa3b, v37
	v_exp_f32_e32 v186, v186
	v_mul_f32_e32 v161, 0xbfb8aa3b, v36
	v_exp_f32_e32 v161, v161
	v_log_f32_e32 v158, v158
	v_add_f32_e32 v161, 1.0, v161
	v_rcp_f32_e32 v161, v161
	v_mul_f32_e32 v159, 0x3f317217, v160
	v_fma_f32 v161, v161, v185, v132
	v_add_f32_e32 v186, 1.0, v186
	v_rcp_f32_e32 v186, v186
	v_mul_f32_e32 v158, 0x3f317217, v158
	v_log_f32_e32 v161, v161
	v_cvt_pk_f16_f32 v158, v159, v158
	v_fma_f32 v159, v186, v184, v133
	v_log_f32_e32 v159, v159
	v_mul_f32_e32 v186, 0xbfb8aa3b, v30
	v_exp_f32_e32 v186, v186
	v_mul_f32_e32 v160, 0x3f317217, v161
	s_nop 0
	v_add_f32_e32 v161, 1.0, v186
	v_mul_f32_e32 v186, 0xbfb8aa3b, v31
	v_rcp_f32_e32 v161, v161
	v_exp_f32_e32 v186, v186
	v_mul_f32_e32 v159, 0x3f317217, v159
	v_cvt_pk_f16_f32 v159, v160, v159
	v_fma_f32 v161, v161, v146, v134
	v_add_f32_e32 v186, 1.0, v186
	v_rcp_f32_e32 v186, v186
	global_store_dwordx4 v[162:163], v[156:159], off offset:256
	v_mul_f32_e32 v160, 0xbfb8aa3b, v33
	v_log_f32_e32 v161, v161
	v_fma_f32 v156, v186, v179, v135
	v_mul_f32_e32 v159, 0xbfb8aa3b, v32
	v_exp_f32_e32 v159, v159
	v_log_f32_e32 v156, v156
	v_exp_f32_e32 v160, v160
	v_add_f32_e32 v159, 1.0, v159
	v_rcp_f32_e32 v159, v159
	v_mul_f32_e32 v157, 0x3f317217, v161
	v_add_f32_e32 v160, 1.0, v160
	v_rcp_f32_e32 v160, v160
	v_fma_f32 v159, v159, v181, v136
	s_nop 0
	v_mul_f32_e32 v156, 0x3f317217, v156
	v_cvt_pk_f16_f32 v156, v157, v156
	v_fma_f32 v157, v160, v180, v137
	v_log_f32_e32 v159, v159
	v_mul_f32_e32 v161, 0xbfb8aa3b, v27
	v_exp_f32_e32 v161, v161
	v_mul_f32_e32 v160, 0xbfb8aa3b, v26
	v_exp_f32_e32 v160, v160
	v_log_f32_e32 v157, v157
	v_add_f32_e32 v160, 1.0, v160
	v_rcp_f32_e32 v160, v160
	v_mul_f32_e32 v158, 0x3f317217, v159
	v_add_f32_e32 v161, 1.0, v161
	v_rcp_f32_e32 v161, v161
	v_fma_f32 v160, v160, v182, v130
	s_nop 0
	v_mul_f32_e32 v157, 0x3f317217, v157
	v_cvt_pk_f16_f32 v157, v158, v157
	v_fma_f32 v158, v161, v183, v131
	v_log_f32_e32 v160, v160
	v_mul_f32_e32 v162, 0xbfb8aa3b, v29
	v_exp_f32_e32 v162, v162
	v_mul_f32_e32 v161, 0xbfb8aa3b, v28
	v_exp_f32_e32 v161, v161
	v_log_f32_e32 v158, v158
	v_add_f32_e32 v161, 1.0, v161
	v_rcp_f32_e32 v161, v161
	v_mul_f32_e32 v159, 0x3f317217, v160
	v_fma_f32 v161, v161, v185, v132
	v_add_f32_e32 v162, 1.0, v162
	v_rcp_f32_e32 v162, v162
	v_mul_f32_e32 v158, 0x3f317217, v158
	v_log_f32_e32 v161, v161
	v_cvt_pk_f16_f32 v158, v159, v158
	v_fma_f32 v159, v162, v184, v133
	v_log_f32_e32 v159, v159
	v_mul_f32_e32 v162, 0xbfb8aa3b, v22
	v_exp_f32_e32 v162, v162
	v_mul_f32_e32 v160, 0x3f317217, v161
	s_nop 0
	v_add_f32_e32 v161, 1.0, v162
	v_mul_f32_e32 v162, 0xbfb8aa3b, v23
	v_rcp_f32_e32 v161, v161
	v_exp_f32_e32 v162, v162
	v_mul_f32_e32 v159, 0x3f317217, v159
	v_cvt_pk_f16_f32 v159, v160, v159
	v_fma_f32 v161, v161, v146, v134
	v_add_f32_e32 v162, 1.0, v162
	v_rcp_f32_e32 v162, v162
	global_store_dwordx4 v[170:171], v[156:159], off offset:256
	v_mul_f32_e32 v160, 0xbfb8aa3b, v25
	v_log_f32_e32 v161, v161
	v_fma_f32 v156, v162, v179, v135
	v_mul_f32_e32 v159, 0xbfb8aa3b, v24
	v_exp_f32_e32 v159, v159
	v_log_f32_e32 v156, v156
	v_exp_f32_e32 v160, v160
	v_add_f32_e32 v159, 1.0, v159
	v_rcp_f32_e32 v159, v159
	v_mul_f32_e32 v157, 0x3f317217, v161
	v_add_f32_e32 v160, 1.0, v160
	v_rcp_f32_e32 v160, v160
	v_fma_f32 v159, v159, v181, v136
	s_nop 0
	v_mul_f32_e32 v156, 0x3f317217, v156
	v_cvt_pk_f16_f32 v156, v157, v156
	v_fma_f32 v157, v160, v180, v137
	v_log_f32_e32 v159, v159
	v_mul_f32_e32 v161, 0xbfb8aa3b, v19
	v_exp_f32_e32 v161, v161
	v_mul_f32_e32 v160, 0xbfb8aa3b, v18
	v_exp_f32_e32 v160, v160
	v_log_f32_e32 v157, v157
	v_add_f32_e32 v160, 1.0, v160
	v_rcp_f32_e32 v160, v160
	v_mul_f32_e32 v158, 0x3f317217, v159
	v_add_f32_e32 v161, 1.0, v161
	v_rcp_f32_e32 v161, v161
	v_fma_f32 v160, v160, v182, v130
	s_nop 0
	v_mul_f32_e32 v157, 0x3f317217, v157
	v_cvt_pk_f16_f32 v157, v158, v157
	v_fma_f32 v158, v161, v183, v131
	v_log_f32_e32 v160, v160
	v_mul_f32_e32 v162, 0xbfb8aa3b, v21
	v_exp_f32_e32 v162, v162
	v_mul_f32_e32 v161, 0xbfb8aa3b, v20
	v_exp_f32_e32 v161, v161
	v_log_f32_e32 v158, v158
	v_add_f32_e32 v161, 1.0, v161
	v_rcp_f32_e32 v161, v161
	v_mul_f32_e32 v159, 0x3f317217, v160
	v_fma_f32 v161, v161, v185, v132
	v_add_f32_e32 v162, 1.0, v162
	v_rcp_f32_e32 v162, v162
	v_mul_f32_e32 v158, 0x3f317217, v158
	v_log_f32_e32 v161, v161
	v_cvt_pk_f16_f32 v158, v159, v158
	v_fma_f32 v159, v162, v184, v133
	v_log_f32_e32 v159, v159
	v_mul_f32_e32 v162, 0xbfb8aa3b, v14
	v_exp_f32_e32 v162, v162
	v_mul_f32_e32 v160, 0x3f317217, v161
	s_nop 0
	v_add_f32_e32 v161, 1.0, v162
	v_mul_f32_e32 v162, 0xbfb8aa3b, v15
	v_rcp_f32_e32 v161, v161
	v_exp_f32_e32 v162, v162
	v_mul_f32_e32 v159, 0x3f317217, v159
	v_cvt_pk_f16_f32 v159, v160, v159
	v_fma_f32 v161, v161, v146, v134
	v_add_f32_e32 v162, 1.0, v162
	v_rcp_f32_e32 v162, v162
	global_store_dwordx4 v[168:169], v[156:159], off offset:256
	v_mul_f32_e32 v160, 0xbfb8aa3b, v17
	v_log_f32_e32 v161, v161
	v_fma_f32 v156, v162, v179, v135
	v_mul_f32_e32 v159, 0xbfb8aa3b, v16
	v_exp_f32_e32 v159, v159
	v_log_f32_e32 v156, v156
	v_exp_f32_e32 v160, v160
	v_add_f32_e32 v159, 1.0, v159
	v_rcp_f32_e32 v159, v159
	v_mul_f32_e32 v157, 0x3f317217, v161
	v_add_f32_e32 v160, 1.0, v160
	v_rcp_f32_e32 v160, v160
	v_fma_f32 v159, v159, v181, v136
	s_nop 0
	v_mul_f32_e32 v156, 0x3f317217, v156
	v_cvt_pk_f16_f32 v156, v157, v156
	v_fma_f32 v157, v160, v180, v137
	v_log_f32_e32 v159, v159
	v_mul_f32_e32 v161, 0xbfb8aa3b, v11
	v_exp_f32_e32 v161, v161
	v_mul_f32_e32 v160, 0xbfb8aa3b, v10
	v_exp_f32_e32 v160, v160
	v_log_f32_e32 v157, v157
	v_add_f32_e32 v160, 1.0, v160
	v_rcp_f32_e32 v160, v160
	v_mul_f32_e32 v158, 0x3f317217, v159
	v_add_f32_e32 v161, 1.0, v161
	v_rcp_f32_e32 v161, v161
	v_fma_f32 v160, v160, v182, v130
	s_nop 0
	v_mul_f32_e32 v157, 0x3f317217, v157
	v_cvt_pk_f16_f32 v157, v158, v157
	v_fma_f32 v158, v161, v183, v131
	v_log_f32_e32 v160, v160
	v_mul_f32_e32 v162, 0xbfb8aa3b, v13
	v_exp_f32_e32 v162, v162
	v_mul_f32_e32 v161, 0xbfb8aa3b, v12
	v_exp_f32_e32 v161, v161
	v_log_f32_e32 v158, v158
	v_add_f32_e32 v161, 1.0, v161
	v_rcp_f32_e32 v161, v161
	v_mul_f32_e32 v159, 0x3f317217, v160
	v_fma_f32 v161, v161, v185, v132
	v_add_f32_e32 v162, 1.0, v162
	v_rcp_f32_e32 v162, v162
	v_mul_f32_e32 v158, 0x3f317217, v158
	v_log_f32_e32 v161, v161
	v_cvt_pk_f16_f32 v158, v159, v158
	v_fma_f32 v159, v162, v184, v133
	v_log_f32_e32 v159, v159
	v_mul_f32_e32 v162, 0xbfb8aa3b, v6
	v_exp_f32_e32 v162, v162
	v_mul_f32_e32 v160, 0x3f317217, v161
	s_nop 0
	v_add_f32_e32 v161, 1.0, v162
	v_mul_f32_e32 v162, 0xbfb8aa3b, v7
	v_rcp_f32_e32 v161, v161
	v_exp_f32_e32 v162, v162
	v_mul_f32_e32 v159, 0x3f317217, v159
	v_cvt_pk_f16_f32 v159, v160, v159
	v_fma_f32 v134, v161, v146, v134
	v_add_f32_e32 v146, 1.0, v162
	v_rcp_f32_e32 v146, v146
	global_store_dwordx4 v[166:167], v[156:159], off offset:256
	v_fma_f32 v135, v146, v179, v135
	s_nop 0
	v_mul_f32_e32 v156, 0xbfb8aa3b, v8
	v_exp_f32_e32 v156, v156
	v_log_f32_e32 v134, v134
	v_mul_f32_e32 v157, 0xbfb8aa3b, v9
	v_exp_f32_e32 v157, v157
	v_add_f32_e32 v156, 1.0, v156
	v_rcp_f32_e32 v156, v156
	v_log_f32_e32 v135, v135
	v_fma_f32 v136, v156, v181, v136
	v_add_f32_e32 v156, 1.0, v157
	v_mul_f32_e32 v134, 0x3f317217, v134
	v_rcp_f32_e32 v156, v156
	s_nop 0
	v_fmac_f32_e32 v137, v156, v180
	v_mul_f32_e32 v156, 0xbfb8aa3b, v3
	v_mul_f32_e32 v135, 0x3f317217, v135
	v_log_f32_e32 v136, v136
	v_mul_f32_e32 v146, 0xbfb8aa3b, v2
	v_exp_f32_e32 v146, v146
	v_cvt_pk_f16_f32 v134, v134, v135
	v_log_f32_e32 v137, v137
	v_add_f32_e32 v146, 1.0, v146
	v_rcp_f32_e32 v146, v146
	v_exp_f32_e32 v156, v156
	v_fma_f32 v130, v146, v182, v130
	v_add_f32_e32 v146, 1.0, v156
	v_mul_f32_e32 v135, 0x3f317217, v136
	v_rcp_f32_e32 v146, v146
	s_nop 0
	v_fma_f32 v131, v146, v183, v131
	s_nop 0
	v_mul_f32_e32 v136, 0x3f317217, v137
	v_log_f32_e32 v130, v130
	v_mul_f32_e32 v137, 0xbfb8aa3b, v4
	v_exp_f32_e32 v137, v137
	v_cvt_pk_f16_f32 v135, v135, v136
	v_log_f32_e32 v131, v131
	v_add_f32_e32 v137, 1.0, v137
	v_mul_f32_e32 v146, 0xbfb8aa3b, v5
	v_rcp_f32_e32 v137, v137
	v_exp_f32_e32 v146, v146
	v_mul_f32_e32 v130, 0x3f317217, v130
	v_fma_f32 v132, v137, v185, v132
	v_add_f32_e32 v137, 1.0, v146
	v_rcp_f32_e32 v137, v137
	v_mul_f32_e32 v131, 0x3f317217, v131
	v_log_f32_e32 v132, v132
	v_fmac_f32_e32 v133, v137, v184
	v_cmp_gt_f32_e64 s[6:7], s93, v133
	v_cvt_pk_f16_f32 v136, v130, v131
	s_nop 0
	v_cndmask_b32_e64 v131, 0, 32, s[6:7]
	v_ldexp_f32 v131, v133, v131
	v_log_f32_e32 v131, v131
	s_nop 1
	v_mul_f32_e32 v130, 0x3f317217, v132
	v_mul_f32_e32 v132, 0x3f317217, v131
	v_fma_f32 v132, v131, s94, -v132
	v_fmac_f32_e32 v132, 0x3377d1cf, v131
	v_fmac_f32_e32 v132, 0x3f317217, v131
	v_cmp_lt_f32_e64 vcc, |v131|, s95
	s_nop 1
	v_cndmask_b32_e32 v131, v131, v132, vcc
	v_cndmask_b32_e64 v132, 0, v178, s[6:7]
	v_sub_f32_e32 v131, v131, v132
	v_cvt_pk_f16_f32 v137, v130, v131
	global_store_dwordx4 v[164:165], v[134:137], off offset:256
